# compressed-branch pass 2: V fragments for the PV MFMAs read early into free registers instead of eight serialized read-wait-MFMA round trips
# speedup vs baseline: 1.0028x; 1.0028x over previous
; __device__ __forceinline__ unsigned cvt_pk_bf16(float lo, float hi) { unsigned r; asm volatile("v_cvt_pk_bf16_f32 %0, %1, %2" : "=v"(r) : "v"(lo), "v"(hi)); return r; }
; __device__ __forceinline__ int swz(int R) { return (R & 2) | ((R & 8) >> 1); }
; __device__ __forceinline__ void pv(f32x4 (&o)[4], const float (&p)[4][4], const unsigned char* Vs, int r, int fq) {
;     bf16x8 pb[2];
; #pragma unroll
;     for (int kc = 0; kc < 2; ++kc) {
;         u32x4 w; w.x = cvt_pk_bf16(p[2 * kc][0], p[2 * kc][1]); w.y = cvt_pk_bf16(p[2 * kc][2], p[2 * kc][3]); w.z = cvt_pk_bf16(p[2 * kc + 1][0], p[2 * kc + 1][1]); w.w = cvt_pk_bf16(p[2 * kc + 1][2], p[2 * kc + 1][3]);
;         pb[kc] = __builtin_bit_cast(bf16x8, w);
;     }
; #pragma unroll
;     for (int df = 0; df < 4; ++df)
; #pragma unroll
;         for (int kc = 0; kc < 2; ++kc) {
;             const int R = prow(df, r);
;             const bf16x8 vf = *(const bf16x8*)(Vs + R * 128 + (((4 * kc + fq) ^ swz(R)) << 4));
;             o[df] = __builtin_amdgcn_mfma_f32_16x16x32_bf16(vf, pb[kc], o[df], 0, 0, 0);
;         }
; }
.LBB0_2329:
	s_or_b64 exec, exec, s[10:11]
	v_cvt_pk_bf16_f32 v76, v61, v63
	v_cvt_pk_bf16_f32 v77, v60, v62
	v_cvt_pk_bf16_f32 v78, v65, v67
	v_cvt_pk_bf16_f32 v79, v64, v66
	v_cvt_pk_bf16_f32 v60, v69, v71
	v_cvt_pk_bf16_f32 v61, v68, v70
	v_cvt_pk_bf16_f32 v62, v73, v75
	v_cvt_pk_bf16_f32 v63, v72, v74
	ds_read_b128 v[64:67], v154 offset:12800
	ds_read_b128 v[68:71], v149 offset:12288
	ds_read_b128 v[72:75], v149 offset:12800
	s_add_i32 s16, s16, -1
	s_add_i32 s14, s14, 1
	s_addk_i32 s15, 0x4000
	s_addk_i32 s4, 0x80
	v_add_u32_e32 v19, 0xfffffc00, v19
	v_add_u32_e32 v147, 64, v147
	v_lshl_add_u64 v[110:111], v[110:111], 0, s[62:63]
	s_cmp_eq_u32 s16, -1
	s_waitcnt lgkmcnt(3)
	v_mfma_f32_16x16x32_bf16 v[28:31], v[232:235], v[76:79], v[28:31]
	v_mfma_f32_16x16x32_bf16 v[28:31], v[236:239], v[60:63], v[28:31]
	v_mfma_f32_16x16x32_bf16 v[24:27], v[240:243], v[76:79], v[24:27]
	v_mfma_f32_16x16x32_bf16 v[24:27], v[244:247], v[60:63], v[24:27]
	v_mfma_f32_16x16x32_bf16 v[44:47], v[248:251], v[76:79], v[44:47]
	s_waitcnt lgkmcnt(2)
	v_mfma_f32_16x16x32_bf16 v[20:23], v[64:67], v[76:79], v[20:23]
	s_waitcnt lgkmcnt(1)
	v_mfma_f32_16x16x32_bf16 v[44:47], v[68:71], v[60:63], v[44:47]
	s_waitcnt lgkmcnt(0)
	v_mfma_f32_16x16x32_bf16 v[20:23], v[72:75], v[60:63], v[20:23]
	s_cbranch_scc1 .LBB0_2430

; __device__ __forceinline__ float dpp_xor1(float x) { return __builtin_bit_cast(float, __builtin_amdgcn_update_dpp(0, __builtin_bit_cast(int, x), 0xB1, 0xF, 0xF, true)); }
; __device__ __forceinline__ float dpp_xor2(float x) { return __builtin_bit_cast(float, __builtin_amdgcn_update_dpp(0, __builtin_bit_cast(int, x), 0x4E, 0xF, 0xF, true)); }
; __device__ __forceinline__ void unitA(unsigned char* lds, PG8_LAS unsigned char* lds3, const Args& a, int b, int g, int T) {
;     ...
;                 for (int f = 0; f < 4; ++f) {
; #pragma unroll
;                     for (int i = 0; i < 4; ++i) v[f][i] = __builtin_amdgcn_exp2f(v[f][i]);
;                     float pa = v[f][0] + v[f][1] + v[f][2] + 0.5f * v[f][3], pb = 0.5f * v[f][3];
;                     pa += dpp_xor1(pa); pa += dpp_xor2(pa); pb += dpp_xor1(pb); pb += dpp_xor2(pb);
;                     if (hl == 0) { const int jj = 16 * ib + 8 * (f >> 1) + 2 * fq + (f & 1); atomicAdd(&imp[qi * IMP_LD + jj], pa); atomicAdd(&imp[qi * IMP_LD + jj + 1], pb); }
;                 }
.LBB0_2376:
	ds_read_b128 v[232:235], v154 offset:8192
	ds_read_b128 v[236:239], v149 offset:8192
	ds_read_b128 v[240:243], v154 offset:8704
	ds_read_b128 v[244:247], v149 offset:8704
	ds_read_b128 v[248:251], v154 offset:12288
	v_exp_f32_e32 v116, v104
	v_exp_f32_e32 v117, v105
	v_exp_f32_e32 v104, v106
	v_exp_f32_e32 v105, v107
	v_add_f32_e32 v106, v117, v116
	v_add_f32_e32 v106, v104, v106
	v_mul_f32_e32 v118, 0.5, v105
	v_fmac_f32_e32 v106, 0.5, v105
	s_nop 0
	v_mov_b32_dpp v118, v118 quad_perm:[1,0,3,2] row_mask:0xf bank_mask:0xf bound_ctrl:1
	v_add_f32_dpp v106, v106, v106 quad_perm:[1,0,3,2] row_mask:0xf bank_mask:0xf bound_ctrl:1
	v_fmac_f32_e32 v118, 0.5, v105
	s_nop 0
	v_mov_b32_dpp v107, v106 quad_perm:[2,3,0,1] row_mask:0xf bank_mask:0xf bound_ctrl:1
	v_mov_b32_dpp v119, v118 quad_perm:[2,3,0,1] row_mask:0xf bank_mask:0xf bound_ctrl:1
	s_and_saveexec_b64 s[12:13], s[8:9]
	s_cbranch_execz .LBB0_2378
	v_add_f32_e32 v106, v106, v107
	v_add_f32_e32 v107, v118, v119
	ds_add_f32 v147, v106
	ds_add_f32 v147, v107 offset:4

; __device__ __forceinline__ unsigned cvt_pk_bf16(float lo, float hi) { unsigned r; asm volatile("v_cvt_pk_bf16_f32 %0, %1, %2" : "=v"(r) : "v"(lo), "v"(hi)); return r; }
; __device__ __forceinline__ int swz(int R) { return (R & 2) | ((R & 8) >> 1); }
; __device__ __forceinline__ void pv(f32x4 (&o)[4], const float (&p)[4][4], const unsigned char* Vs, int r, int fq) {
;     bf16x8 pb[2];
; #pragma unroll
;     for (int kc = 0; kc < 2; ++kc) {
;         u32x4 w; w.x = cvt_pk_bf16(p[2 * kc][0], p[2 * kc][1]); w.y = cvt_pk_bf16(p[2 * kc][2], p[2 * kc][3]); w.z = cvt_pk_bf16(p[2 * kc + 1][0], p[2 * kc + 1][1]); w.w = cvt_pk_bf16(p[2 * kc + 1][2], p[2 * kc + 1][3]);
;         pb[kc] = __builtin_bit_cast(bf16x8, w);
;     }
; #pragma unroll
;     for (int df = 0; df < 4; ++df)
; #pragma unroll
;         for (int kc = 0; kc < 2; ++kc) {
;             const int R = prow(df, r);
;             const bf16x8 vf = *(const bf16x8*)(Vs + R * 128 + (((4 * kc + fq) ^ swz(R)) << 4));
;             o[df] = __builtin_amdgcn_mfma_f32_16x16x32_bf16(vf, pb[kc], o[df], 0, 0, 0);
;         }
; }
.LBB0_2384:
	s_or_b64 exec, exec, s[12:13]
	v_cvt_pk_bf16_f32 v116, v116, v117
	v_cvt_pk_bf16_f32 v117, v104, v105
	v_cvt_pk_bf16_f32 v118, v106, v107
	v_cvt_pk_bf16_f32 v119, v100, v101
	v_cvt_pk_bf16_f32 v94, v102, v103
	v_cvt_pk_bf16_f32 v95, v96, v97
	v_cvt_pk_bf16_f32 v96, v98, v99
	v_cvt_pk_bf16_f32 v97, v92, v93
	ds_read_b128 v[98:101], v149 offset:12288
	s_mov_b64 s[12:13], -1
	s_andn2_b64 vcc, exec, s[10:11]
	s_waitcnt lgkmcnt(1)
	v_mfma_f32_16x16x32_bf16 v[36:39], v[232:235], v[116:119], v[36:39]
	ds_read_b128 v[232:235], v154 offset:12800
	v_mfma_f32_16x16x32_bf16 v[36:39], v[236:239], v[94:97], v[36:39]
	ds_read_b128 v[236:239], v149 offset:12800
	v_mfma_f32_16x16x32_bf16 v[48:51], v[240:243], v[116:119], v[48:51]
	v_mfma_f32_16x16x32_bf16 v[48:51], v[244:247], v[94:97], v[48:51]
	v_mfma_f32_16x16x32_bf16 v[32:35], v[248:251], v[116:119], v[32:35]
	s_waitcnt lgkmcnt(2)
	v_mfma_f32_16x16x32_bf16 v[32:35], v[98:101], v[94:97], v[32:35]
	s_waitcnt lgkmcnt(1)
	v_mfma_f32_16x16x32_bf16 v[40:43], v[232:235], v[116:119], v[40:43]
	s_waitcnt lgkmcnt(0)
	v_mfma_f32_16x16x32_bf16 v[40:43], v[236:239], v[94:97], v[40:43]
	s_cbranch_vccnz .LBB0_2386
	v_mfma_f32_16x16x32_bf16 v[92:95], v[64:67], v[10:13], v[56:59]
	s_mov_b64 s[12:13], 0
	v_mfma_f32_16x16x32_bf16 v[104:107], v[84:87], v[14:17], v[92:95]
	v_mfma_f32_16x16x32_bf16 v[92:95], v[68:71], v[10:13], v[56:59]
	v_mfma_f32_16x16x32_bf16 v[100:103], v[72:75], v[14:17], v[92:95]
	v_mfma_f32_16x16x32_bf16 v[92:95], v[76:79], v[10:13], v[56:59]
	v_mfma_f32_16x16x32_bf16 v[96:99], v[88:91], v[14:17], v[92:95]
	v_mfma_f32_16x16x32_bf16 v[92:95], v[80:83], v[10:13], v[56:59]
	v_mfma_f32_16x16x32_bf16 v[92:95], v[60:63], v[14:17], v[92:95]

; __device__ __forceinline__ float dpp_xor1(float x) { return __builtin_bit_cast(float, __builtin_amdgcn_update_dpp(0, __builtin_bit_cast(int, x), 0xB1, 0xF, 0xF, true)); }
; __device__ __forceinline__ float dpp_xor2(float x) { return __builtin_bit_cast(float, __builtin_amdgcn_update_dpp(0, __builtin_bit_cast(int, x), 0x4E, 0xF, 0xF, true)); }
; __device__ __forceinline__ void unitA(unsigned char* lds, PG8_LAS unsigned char* lds3, const Args& a, int b, int g, int T) {
;     ...
;                 for (int f = 0; f < 4; ++f) {
; #pragma unroll
;                     for (int i = 0; i < 4; ++i) v[f][i] = __builtin_amdgcn_exp2f(v[f][i]);
;                     float pa = v[f][0] + v[f][1] + v[f][2] + 0.5f * v[f][3], pb = 0.5f * v[f][3];
;                     pa += dpp_xor1(pa); pa += dpp_xor2(pa); pb += dpp_xor1(pb); pb += dpp_xor2(pb);
;                     if (hl == 0) { const int jj = 16 * ib + 8 * (f >> 1) + 2 * fq + (f & 1); atomicAdd(&imp[qi * IMP_LD + jj], pa); atomicAdd(&imp[qi * IMP_LD + jj + 1], pb); }
;                 }
.LBB0_2420:
	ds_read_b128 v[232:235], v154 offset:8192
	ds_read_b128 v[236:239], v149 offset:8192
	ds_read_b128 v[240:243], v154 offset:8704
	ds_read_b128 v[244:247], v149 offset:8704
	ds_read_b128 v[248:251], v154 offset:12288
	v_exp_f32_e32 v61, v104
	v_exp_f32_e32 v63, v105
	v_exp_f32_e32 v60, v106
	v_exp_f32_e32 v62, v107
	v_add_f32_e32 v64, v63, v61
	v_add_f32_e32 v64, v60, v64
	v_mul_f32_e32 v66, 0.5, v62
	v_fmac_f32_e32 v64, 0.5, v62
	s_nop 0
	v_mov_b32_dpp v66, v66 quad_perm:[1,0,3,2] row_mask:0xf bank_mask:0xf bound_ctrl:1
	v_add_f32_dpp v64, v64, v64 quad_perm:[1,0,3,2] row_mask:0xf bank_mask:0xf bound_ctrl:1
	v_fmac_f32_e32 v66, 0.5, v62
	s_nop 0
	v_mov_b32_dpp v65, v64 quad_perm:[2,3,0,1] row_mask:0xf bank_mask:0xf bound_ctrl:1
	v_mov_b32_dpp v67, v66 quad_perm:[2,3,0,1] row_mask:0xf bank_mask:0xf bound_ctrl:1
	s_and_saveexec_b64 s[10:11], s[8:9]
	s_cbranch_execz .LBB0_2422
	v_add_f32_e32 v64, v64, v65
	v_add_f32_e32 v65, v66, v67
	ds_add_f32 v147, v64 offset:2064
	ds_add_f32 v147, v65 offset:2068
